# mem_attn: s_setprio 1 over the two MFMA sections (QK and PV), 0 in between and after (timing-only)
# speedup vs baseline: 1.0015x; 1.0015x over previous
; __device__ __forceinline__ float ozero() { float z = 0.f; asm volatile("" : "+v"(z)); return z; }
; __device__ __forceinline__ int otid() { return otid_full() & 255; }
; __device__ __forceinline__ f32x4 mfma16(bf16x8 a, bf16x8 b, f32x4 c) { return __builtin_amdgcn_mfma_f32_16x16x32_bf16(a, b, c, 0, 0, 0); }
; __device__ __forceinline__ void mem_attn(const Params& p, int layer, int task) {
;   const int tid = otid(), lane = tid & 63, h = tid >> 6;
;   const int n16 = lane & 15, kq = lane >> 4;
;   const size_t tok0 = (size_t)task * 16; const int b = (int)(tok0 >> 14);
;   const bf* mk = p.MK + (((size_t)layer * 2 + b) * 4 + h) * 256 * 64;
;   const bf* mvt = p.MVT + (((size_t)layer * 2 + b) * 4 + h) * 64 * 256;
;   bf16x8 qf[2];
;   {
;     const bf* qp = p.P + (tok0 + n16) * PW + C_MEQ + h * 64 + 8 * kq;
;     qf[0] = *(const bf16x8*)qp; qf[1] = *(const bf16x8*)(qp + 32);
;   }
;   f32x4 st[16];
; #pragma unroll
;   for (int kb = 0; kb < 16; kb++) {
;     const bf* kp = mk + (size_t)(16 * kb + n16) * 64 + 8 * kq;
;     bf16x8 a0 = *(const bf16x8*)kp, a1 = *(const bf16x8*)(kp + 32);
;     const float z_ = ozero(); f32x4 acc = {z_, z_, z_, z_};
;     acc = mfma16(a0, qf[0], acc); acc = mfma16(a1, qf[1], acc);
;     st[kb] = acc * 0.125f;
; __device__ __forceinline__ void phaseB(const Params& p, int layer, char* sm0) {
;     ...
;   for (int t = VB; t < total; t += G2) {
;     if (t < 512) ssd_pass1(p, layer, t, sm);
;     else if (t < 2560) s5_pass1(p, layer, t - 512, sm);
;     else mem_attn(p, layer, t - 2560);
.LBB0_472:
	s_cmpk_gt_i32 s31, 0x1ff
	s_mov_b64 s[0:1], -1
	s_cbranch_scc0 .LBB0_480
	s_cmpk_gt_u32 s31, 0x9ff
	s_cbranch_scc0 .LBB0_475
	s_add_i32 s0, s31, 0xfffff600
	s_lshr_b32 s1, s0, 8
	v_mov_b32_e32 v2, v203
	s_and_b32 s1, s1, 4
	s_or_b32 s1, s1, s27
	v_lshrrev_b32_e32 v0, 6, v2
	v_readlane_b32 s52, v253, 3
	v_and_b32_e32 v83, 15, v2
	v_and_or_b32 v0, v0, 3, s1
	v_readlane_b32 s62, v253, 13
	v_readlane_b32 s63, v253, 14
	v_bfe_u32 v3, v2, 4, 2
	v_lshlrev_b32_e32 v144, 15, v0
	v_lshl_or_b32 v82, s0, 4, v83
	v_mov_b64_e32 v[0:1], s[62:63]
	v_and_b32_e32 v2, 0xc0, v2
	v_readlane_b32 s4, v253, 22
	v_mad_u64_u32 v[0:1], s[0:1], v82, s96, v[0:1]
	v_lshlrev_b32_e32 v16, 1, v2
	v_mov_b32_e32 v17, v145
	v_readlane_b32 s6, v253, 24
	v_readlane_b32 s7, v253, 25
	v_lshlrev_b32_e32 v10, 4, v3
	v_mov_b32_e32 v11, v145
	v_lshl_add_u64 v[20:21], v[0:1], 0, v[16:17]
	v_lshl_add_u64 v[8:9], s[6:7], 0, v[144:145]
	v_lshl_add_u64 v[0:1], v[20:21], 0, v[10:11]
	s_mov_b64 s[0:1], 0x28c0
	s_movk_i32 s2, 0x2000
	v_lshlrev_b32_e32 v18, 3, v3
	v_lshl_add_u64 v[2:3], v[0:1], 0, s[0:1]
	v_add_co_u32_e32 v0, vcc, s2, v0
	v_lshl_add_u64 v[8:9], v[8:9], 0, v[10:11]
	v_lshlrev_b32_e32 v10, 7, v83
	v_addc_co_u32_e32 v1, vcc, 0, v1, vcc
	v_lshl_add_u64 v[8:9], v[8:9], 0, v[10:11]
	global_load_dwordx4 v[4:7], v[0:1], off offset:2240
	s_nop 0
	global_load_dwordx4 v[0:3], v[2:3], off offset:64
	s_nop 0
	v_and_b32_e32 v102, 15, v202
	v_lshrrev_b32_e32 v103, 4, v202
	v_lshlrev_b32_e32 v107, 2, v103
	v_lshl_or_b32 v107, v102, 4, v107
	v_lshlrev_b32_e32 v102, 7, v102
	v_lshl_add_u32 v102, v103, 4, v102
	v_lshrrev_b32_e32 v103, 2, v202
	v_lshlrev_b32_e32 v103, 7, v103
	v_sub_u32_e32 v102, v103, v102
	v_and_b32_e32 v103, 3, v202
	v_lshl_add_u32 v102, v103, 4, v102
	v_ashrrev_i32_e32 v103, 31, v102
	v_lshl_add_u64 v[104:105], v[8:9], 0, v[102:103]
	v_mov_b32_e32 v102, v104
	v_mov_b32_e32 v103, v105
	v_mov_b32_e32 v104, 0x1000
	v_mov_b32_e32 v105, 0
	v_lshl_add_u64 v[146:147], v[102:103], 0, v[104:105]
	v_mov_b32_e32 v104, 0x2000
	v_lshl_add_u64 v[196:197], v[146:147], 0, v[104:105]
	v_lshl_add_u64 v[198:199], v[196:197], 0, v[104:105]
	v_lshl_add_u64 v[200:201], v[198:199], 0, v[104:105]
	global_load_dwordx4 v[108:111], v[146:147], off offset:-4096
	global_load_dwordx4 v[112:115], v[146:147], off offset:-4032
	global_load_dwordx4 v[116:119], v[146:147], off offset:-2048
	global_load_dwordx4 v[120:123], v[146:147], off offset:-1984
	global_load_dwordx4 v[124:127], v[146:147], off
	global_load_dwordx4 v[128:131], v[146:147], off offset:64
	global_load_dwordx4 v[132:135], v[146:147], off offset:2048
	global_load_dwordx4 v[136:139], v[146:147], off offset:2112
	global_load_dwordx4 v[140:143], v[196:197], off offset:-4096
	global_load_dwordx4 v[148:151], v[196:197], off offset:-4032
	global_load_dwordx4 v[152:155], v[196:197], off offset:-2048
	global_load_dwordx4 v[156:159], v[196:197], off offset:-1984
	global_load_dwordx4 v[160:163], v[196:197], off
	global_load_dwordx4 v[164:167], v[196:197], off offset:64
	global_load_dwordx4 v[168:171], v[196:197], off offset:2048
	global_load_dwordx4 v[172:175], v[196:197], off offset:2112
	global_load_dwordx4 v[176:179], v[198:199], off offset:-4096
	global_load_dwordx4 v[180:183], v[198:199], off offset:-4032
	global_load_dwordx4 v[184:187], v[198:199], off offset:-2048
	global_load_dwordx4 v[188:191], v[198:199], off offset:-1984
	global_load_dwordx4 v[192:195], v[198:199], off
	v_mov_b32_e32 v26, v145
	s_mov_b32 s6, 0x3e000000
	v_mov_b32_e32 v27, v26
	v_mov_b32_e32 v28, v26
	v_mov_b32_e32 v29, v26
	v_mov_b32_e32 v32, v145
	s_movk_i32 s4, 0x1000
	v_add_co_u32_e32 v14, vcc, s4, v8
	v_mov_b32_e32 v38, v145
	s_nop 0
	v_addc_co_u32_e32 v15, vcc, 0, v9, vcc
	v_add_co_u32_e32 v48, vcc, s2, v8
	v_mov_b32_e32 v44, v145
	s_nop 0
	v_addc_co_u32_e32 v49, vcc, 0, v9, vcc
	s_movk_i32 s0, 0x3000
	v_add_co_u32_e32 v54, vcc, s0, v8
	s_movk_i32 s0, 0x4000
	s_nop 0
	v_addc_co_u32_e32 v55, vcc, 0, v9, vcc
	v_mov_b32_e32 v56, v145
	v_mov_b32_e32 v64, v145
	v_mov_b32_e32 v72, v145
	v_readlane_b32 s8, v253, 26
	v_readlane_b32 s9, v253, 27
	v_mov_b32_e32 v19, v145
	s_mov_b32 s3, 0xffff
	v_readlane_b32 s64, v253, 15
	v_readlane_b32 s65, v253, 16
	v_readlane_b32 s5, v253, 23
	v_readlane_b32 s10, v253, 28
	v_readlane_b32 s11, v253, 29
	v_readlane_b32 s12, v253, 30
	v_readlane_b32 s13, v253, 31
	v_readlane_b32 s14, v253, 32
	v_readlane_b32 s15, v253, 33
	v_readlane_b32 s16, v253, 34
	v_readlane_b32 s17, v253, 35
	v_readlane_b32 s18, v253, 36
	v_readlane_b32 s19, v253, 37
	v_readlane_b32 s53, v253, 4
	v_readlane_b32 s54, v253, 5
	v_readlane_b32 s55, v253, 6
	v_readlane_b32 s56, v253, 7
	s_waitcnt vmcnt(20)
	ds_bpermute_b32 v108, v107, v108
	ds_bpermute_b32 v109, v107, v109
	ds_bpermute_b32 v110, v107, v110
	ds_bpermute_b32 v111, v107, v111
	s_waitcnt vmcnt(19)
	ds_bpermute_b32 v112, v107, v112
	ds_bpermute_b32 v113, v107, v113
	ds_bpermute_b32 v114, v107, v114
	ds_bpermute_b32 v115, v107, v115
	s_waitcnt lgkmcnt(4)
	s_setprio 1
	v_mfma_f32_16x16x32_bf16 v[10:13], v[108:111], v[4:7], v[26:29]
	global_load_dwordx4 v[108:111], v[198:199], off offset:64
	v_readlane_b32 s57, v253, 8
	v_readlane_b32 s58, v253, 9
	v_readlane_b32 s59, v253, 10
	s_waitcnt vmcnt(19)
	ds_bpermute_b32 v116, v107, v116
	ds_bpermute_b32 v117, v107, v117
	ds_bpermute_b32 v118, v107, v118
	ds_bpermute_b32 v119, v107, v119
	s_waitcnt lgkmcnt(4)
	v_mfma_f32_16x16x32_bf16 v[10:13], v[112:115], v[0:3], v[10:13]
	global_load_dwordx4 v[112:115], v[198:199], off offset:2048
	v_readlane_b32 s60, v253, 11
	v_readlane_b32 s61, v253, 12
	v_readlane_b32 s66, v253, 17
	v_readlane_b32 s67, v253, 18
	s_nop 3
	v_pk_mul_f32 v[22:23], v[12:13], s[6:7] op_sel_hi:[1,0]
	v_pk_mul_f32 v[26:27], v[10:11], s[6:7] op_sel_hi:[1,0]
	s_nop 0
	v_mov_b32_e32 v33, v32
	v_mov_b32_e32 v34, v32
	v_mov_b32_e32 v35, v32
	s_nop 0
	s_waitcnt vmcnt(19)
; __device__ __forceinline__ float ozero() { float z = 0.f; asm volatile("" : "+v"(z)); return z; }
; __device__ __forceinline__ f32x4 mfma16(bf16x8 a, bf16x8 b, f32x4 c) { return __builtin_amdgcn_mfma_f32_16x16x32_bf16(a, b, c, 0, 0, 0); }
; __device__ __forceinline__ void mem_attn(const Params& p, int layer, int task) {
;     ...
; #pragma unroll
;   for (int kb = 0; kb < 16; kb++) {
;     const bf* kp = mk + (size_t)(16 * kb + n16) * 64 + 8 * kq;
;     bf16x8 a0 = *(const bf16x8*)kp, a1 = *(const bf16x8*)(kp + 32);
;     const float z_ = ozero(); f32x4 acc = {z_, z_, z_, z_};
;     acc = mfma16(a0, qf[0], acc); acc = mfma16(a1, qf[1], acc);
;     st[kb] = acc * 0.125f;
	ds_bpermute_b32 v120, v107, v120
	ds_bpermute_b32 v121, v107, v121
	ds_bpermute_b32 v122, v107, v122
	ds_bpermute_b32 v123, v107, v123
	s_waitcnt lgkmcnt(4)
	v_mfma_f32_16x16x32_bf16 v[10:13], v[116:119], v[4:7], v[32:35]
	global_load_dwordx4 v[116:119], v[198:199], off offset:2112
	s_nop 2
	v_mov_b32_e32 v34, v145
	s_waitcnt vmcnt(19)
	ds_bpermute_b32 v124, v107, v124
	ds_bpermute_b32 v125, v107, v125
	ds_bpermute_b32 v126, v107, v126
	ds_bpermute_b32 v127, v107, v127
	s_waitcnt lgkmcnt(4)
	v_mfma_f32_16x16x32_bf16 v[10:13], v[120:123], v[0:3], v[10:13]
	global_load_dwordx4 v[120:123], v[200:201], off offset:-4096
	s_nop 7
	v_pk_mul_f32 v[24:25], v[12:13], s[6:7] op_sel_hi:[1,0]
	v_pk_mul_f32 v[28:29], v[10:11], s[6:7] op_sel_hi:[1,0]
	s_nop 0
	v_mov_b32_e32 v35, v34
	v_mov_b32_e32 v36, v34
	v_mov_b32_e32 v37, v34
	s_nop 0
	s_waitcnt vmcnt(19)
	ds_bpermute_b32 v128, v107, v128
	ds_bpermute_b32 v129, v107, v129
	ds_bpermute_b32 v130, v107, v130
	ds_bpermute_b32 v131, v107, v131
	s_waitcnt lgkmcnt(4)
	v_mfma_f32_16x16x32_bf16 v[10:13], v[124:127], v[4:7], v[34:37]
	global_load_dwordx4 v[124:127], v[200:201], off offset:-4032
	s_waitcnt vmcnt(19)
	ds_bpermute_b32 v132, v107, v132
	ds_bpermute_b32 v133, v107, v133
	ds_bpermute_b32 v134, v107, v134
	ds_bpermute_b32 v135, v107, v135
	s_waitcnt lgkmcnt(4)
	v_mfma_f32_16x16x32_bf16 v[10:13], v[128:131], v[0:3], v[10:13]
	global_load_dwordx4 v[128:131], v[200:201], off offset:-2048
	s_nop 7
	v_pk_mul_f32 v[30:31], v[12:13], s[6:7] op_sel_hi:[1,0]
	v_pk_mul_f32 v[36:37], v[10:11], s[6:7] op_sel_hi:[1,0]
	s_nop 0
	v_mov_b32_e32 v39, v38
	v_mov_b32_e32 v40, v38
	v_mov_b32_e32 v41, v38
	s_nop 0
	s_waitcnt vmcnt(19)
	ds_bpermute_b32 v136, v107, v136
	ds_bpermute_b32 v137, v107, v137
	ds_bpermute_b32 v138, v107, v138
	ds_bpermute_b32 v139, v107, v139
	s_waitcnt lgkmcnt(4)
	v_mfma_f32_16x16x32_bf16 v[10:13], v[132:135], v[4:7], v[38:41]
	global_load_dwordx4 v[132:135], v[200:201], off offset:-1984
	s_waitcnt vmcnt(19)
	ds_bpermute_b32 v140, v107, v140
	ds_bpermute_b32 v141, v107, v141
	ds_bpermute_b32 v142, v107, v142
	ds_bpermute_b32 v143, v107, v143
	s_waitcnt lgkmcnt(4)
	v_mfma_f32_16x16x32_bf16 v[10:13], v[136:139], v[0:3], v[10:13]
	global_load_dwordx4 v[136:139], v[200:201], off
	s_nop 7
	v_pk_mul_f32 v[32:33], v[12:13], s[6:7] op_sel_hi:[1,0]
	v_pk_mul_f32 v[38:39], v[10:11], s[6:7] op_sel_hi:[1,0]
	s_nop 0
	v_mov_b32_e32 v45, v44
	v_mov_b32_e32 v46, v44
	v_mov_b32_e32 v47, v44
	s_nop 0
	s_waitcnt vmcnt(19)
	ds_bpermute_b32 v148, v107, v148
	ds_bpermute_b32 v149, v107, v149
	ds_bpermute_b32 v150, v107, v150
	ds_bpermute_b32 v151, v107, v151
	s_waitcnt lgkmcnt(4)
	v_mfma_f32_16x16x32_bf16 v[10:13], v[140:143], v[4:7], v[44:47]
	global_load_dwordx4 v[140:143], v[200:201], off offset:64
	s_waitcnt vmcnt(19)
	ds_bpermute_b32 v152, v107, v152
	ds_bpermute_b32 v153, v107, v153
	ds_bpermute_b32 v154, v107, v154
	ds_bpermute_b32 v155, v107, v155
	s_waitcnt lgkmcnt(4)
	v_mfma_f32_16x16x32_bf16 v[10:13], v[148:151], v[0:3], v[10:13]
	global_load_dwordx4 v[148:151], v[200:201], off offset:2048
	s_nop 7
	v_pk_mul_f32 v[34:35], v[12:13], s[6:7] op_sel_hi:[1,0]
	v_pk_mul_f32 v[42:43], v[10:11], s[6:7] op_sel_hi:[1,0]
	v_mov_b32_e32 v48, v145
	s_nop 0
	v_mov_b32_e32 v49, v48
	v_mov_b32_e32 v50, v48
	v_mov_b32_e32 v51, v48
	s_nop 0
	s_waitcnt vmcnt(19)
	ds_bpermute_b32 v156, v107, v156
	ds_bpermute_b32 v157, v107, v157
	ds_bpermute_b32 v158, v107, v158
	ds_bpermute_b32 v159, v107, v159
	s_waitcnt lgkmcnt(4)
	v_mfma_f32_16x16x32_bf16 v[10:13], v[152:155], v[4:7], v[48:51]
	global_load_dwordx4 v[152:155], v[200:201], off offset:2112
	s_nop 2
	v_mov_b32_e32 v50, v145
	s_waitcnt vmcnt(19)
	ds_bpermute_b32 v160, v107, v160
	ds_bpermute_b32 v161, v107, v161
	ds_bpermute_b32 v162, v107, v162
	ds_bpermute_b32 v163, v107, v163
	s_waitcnt lgkmcnt(4)
	v_mfma_f32_16x16x32_bf16 v[10:13], v[156:159], v[0:3], v[10:13]
	s_nop 7
	v_pk_mul_f32 v[44:45], v[10:11], s[6:7] op_sel_hi:[1,0]
	v_add_co_u32_e32 v10, vcc, s0, v8
	v_pk_mul_f32 v[40:41], v[12:13], s[6:7] op_sel_hi:[1,0]
	s_nop 0
	v_addc_co_u32_e32 v11, vcc, 0, v9, vcc
	s_movk_i32 s0, 0x6000
	v_mov_b32_e32 v51, v50
	v_mov_b32_e32 v52, v50
	v_mov_b32_e32 v53, v50
	s_nop 0
	s_waitcnt vmcnt(18)
	ds_bpermute_b32 v164, v107, v164
	ds_bpermute_b32 v165, v107, v165
	ds_bpermute_b32 v166, v107, v166
	ds_bpermute_b32 v167, v107, v167
	s_waitcnt lgkmcnt(4)
	v_mfma_f32_16x16x32_bf16 v[12:15], v[160:163], v[4:7], v[50:53]
	s_waitcnt vmcnt(17)
	ds_bpermute_b32 v168, v107, v168
	ds_bpermute_b32 v169, v107, v169
	ds_bpermute_b32 v170, v107, v170
	ds_bpermute_b32 v171, v107, v171
	s_waitcnt lgkmcnt(4)
	v_mfma_f32_16x16x32_bf16 v[12:15], v[164:167], v[0:3], v[12:15]
	s_nop 7
	v_pk_mul_f32 v[46:47], v[14:15], s[6:7] op_sel_hi:[1,0]
	v_pk_mul_f32 v[50:51], v[12:13], s[6:7] op_sel_hi:[1,0]
	s_nop 0
	s_nop 0
	v_mov_b32_e32 v57, v56
	v_mov_b32_e32 v58, v56
	v_mov_b32_e32 v59, v56
	s_nop 0
	s_waitcnt vmcnt(16)
	ds_bpermute_b32 v172, v107, v172
	ds_bpermute_b32 v173, v107, v173
	ds_bpermute_b32 v174, v107, v174
	ds_bpermute_b32 v175, v107, v175
	s_waitcnt lgkmcnt(4)
	v_mfma_f32_16x16x32_bf16 v[12:15], v[168:171], v[4:7], v[56:59]
	s_nop 2
	v_mov_b32_e32 v58, v145
	s_waitcnt vmcnt(15)
	ds_bpermute_b32 v176, v107, v176
	ds_bpermute_b32 v177, v107, v177
	ds_bpermute_b32 v178, v107, v178
	ds_bpermute_b32 v179, v107, v179
	s_waitcnt lgkmcnt(4)
	v_mfma_f32_16x16x32_bf16 v[12:15], v[172:175], v[0:3], v[12:15]
	s_nop 7
	v_pk_mul_f32 v[48:49], v[14:15], s[6:7] op_sel_hi:[1,0]
	v_pk_mul_f32 v[52:53], v[12:13], s[6:7] op_sel_hi:[1,0]
	s_nop 0
	v_mov_b32_e32 v59, v58
	v_mov_b32_e32 v60, v58
	v_mov_b32_e32 v61, v58
	s_nop 0
	s_waitcnt vmcnt(14)
; __device__ __forceinline__ float ozero() { float z = 0.f; asm volatile("" : "+v"(z)); return z; }
; __device__ __forceinline__ f32x4 mfma16(bf16x8 a, bf16x8 b, f32x4 c) { return __builtin_amdgcn_mfma_f32_16x16x32_bf16(a, b, c, 0, 0, 0); }
; __device__ __forceinline__ void mem_attn(const Params& p, int layer, int task) {
;     ...
; #pragma unroll
;   for (int kb = 0; kb < 16; kb++) {
;     const bf* kp = mk + (size_t)(16 * kb + n16) * 64 + 8 * kq;
;     bf16x8 a0 = *(const bf16x8*)kp, a1 = *(const bf16x8*)(kp + 32);
;     const float z_ = ozero(); f32x4 acc = {z_, z_, z_, z_};
;     acc = mfma16(a0, qf[0], acc); acc = mfma16(a1, qf[1], acc);
;     st[kb] = acc * 0.125f;
	ds_bpermute_b32 v180, v107, v180
	ds_bpermute_b32 v181, v107, v181
	ds_bpermute_b32 v182, v107, v182
	ds_bpermute_b32 v183, v107, v183
	s_waitcnt lgkmcnt(4)
	v_mfma_f32_16x16x32_bf16 v[12:15], v[176:179], v[4:7], v[58:61]
	s_waitcnt vmcnt(13)
	ds_bpermute_b32 v184, v107, v184
	ds_bpermute_b32 v185, v107, v185
	ds_bpermute_b32 v186, v107, v186
	ds_bpermute_b32 v187, v107, v187
	s_waitcnt lgkmcnt(4)
	v_mfma_f32_16x16x32_bf16 v[12:15], v[180:183], v[0:3], v[12:15]
	s_nop 7
	v_pk_mul_f32 v[54:55], v[14:15], s[6:7] op_sel_hi:[1,0]
	v_pk_mul_f32 v[58:59], v[12:13], s[6:7] op_sel_hi:[1,0]
	s_nop 0
	v_mov_b32_e32 v65, v64
	v_mov_b32_e32 v66, v64
	v_mov_b32_e32 v67, v64
	s_nop 0
	s_waitcnt vmcnt(12)
	ds_bpermute_b32 v188, v107, v188
	ds_bpermute_b32 v189, v107, v189
	ds_bpermute_b32 v190, v107, v190
	ds_bpermute_b32 v191, v107, v191
	s_waitcnt lgkmcnt(4)
	v_mfma_f32_16x16x32_bf16 v[10:13], v[184:187], v[4:7], v[64:67]
	v_add_co_u32_e32 v14, vcc, s43, v8
	s_nop 1
	v_mov_b32_e32 v66, v145
	s_waitcnt vmcnt(11)
	ds_bpermute_b32 v192, v107, v192
	ds_bpermute_b32 v193, v107, v193
	ds_bpermute_b32 v194, v107, v194
	ds_bpermute_b32 v195, v107, v195
	s_waitcnt lgkmcnt(4)
	v_mfma_f32_16x16x32_bf16 v[10:13], v[188:191], v[0:3], v[10:13]
	v_addc_co_u32_e32 v15, vcc, 0, v9, vcc
	v_add_co_u32_e32 v78, vcc, s0, v8
	s_mov_b32 s0, 0xff61b1e6
	s_nop 0
	v_addc_co_u32_e32 v79, vcc, 0, v9, vcc
	s_nop 2
	v_pk_mul_f32 v[56:57], v[12:13], s[6:7] op_sel_hi:[1,0]
	v_pk_mul_f32 v[60:61], v[10:11], s[6:7] op_sel_hi:[1,0]
	v_add_co_u32_e32 v84, vcc, s47, v8
	v_mov_b32_e32 v67, v66
	v_mov_b32_e32 v68, v66
	v_mov_b32_e32 v69, v66
	v_addc_co_u32_e32 v85, vcc, 0, v9, vcc
	s_waitcnt vmcnt(10)
	ds_bpermute_b32 v108, v107, v108
	ds_bpermute_b32 v109, v107, v109
	ds_bpermute_b32 v110, v107, v110
	ds_bpermute_b32 v111, v107, v111
	s_waitcnt lgkmcnt(4)
	v_mfma_f32_16x16x32_bf16 v[10:13], v[192:195], v[4:7], v[66:69]
	s_waitcnt vmcnt(9)
	ds_bpermute_b32 v112, v107, v112
	ds_bpermute_b32 v113, v107, v113
	ds_bpermute_b32 v114, v107, v114
	ds_bpermute_b32 v115, v107, v115
	s_waitcnt lgkmcnt(4)
	v_mfma_f32_16x16x32_bf16 v[10:13], v[108:111], v[0:3], v[10:13]
	s_nop 7
	v_pk_mul_f32 v[62:63], v[12:13], s[6:7] op_sel_hi:[1,0]
	v_pk_mul_f32 v[66:67], v[10:11], s[6:7] op_sel_hi:[1,0]
	s_nop 0
	v_mov_b32_e32 v73, v72
	v_mov_b32_e32 v74, v72
	v_mov_b32_e32 v75, v72
	s_nop 0
	s_waitcnt vmcnt(8)
	ds_bpermute_b32 v116, v107, v116
	ds_bpermute_b32 v117, v107, v117
	ds_bpermute_b32 v118, v107, v118
	ds_bpermute_b32 v119, v107, v119
	s_waitcnt lgkmcnt(4)
	v_mfma_f32_16x16x32_bf16 v[10:13], v[112:115], v[4:7], v[72:75]
	s_nop 2
	v_mov_b32_e32 v74, v145
	s_waitcnt vmcnt(7)
	ds_bpermute_b32 v120, v107, v120
	ds_bpermute_b32 v121, v107, v121
	ds_bpermute_b32 v122, v107, v122
	ds_bpermute_b32 v123, v107, v123
	s_waitcnt lgkmcnt(4)
	v_mfma_f32_16x16x32_bf16 v[10:13], v[116:119], v[0:3], v[10:13]
	s_nop 7
	v_pk_mul_f32 v[64:65], v[12:13], s[6:7] op_sel_hi:[1,0]
	v_pk_mul_f32 v[68:69], v[10:11], s[6:7] op_sel_hi:[1,0]
	s_nop 0
	v_mov_b32_e32 v75, v74
	v_mov_b32_e32 v76, v74
	v_mov_b32_e32 v77, v74
	s_nop 0
	s_waitcnt vmcnt(6)
	ds_bpermute_b32 v124, v107, v124
	ds_bpermute_b32 v125, v107, v125
	ds_bpermute_b32 v126, v107, v126
	ds_bpermute_b32 v127, v107, v127
	s_waitcnt lgkmcnt(4)
	v_mfma_f32_16x16x32_bf16 v[10:13], v[120:123], v[4:7], v[74:77]
	s_waitcnt vmcnt(5)
	ds_bpermute_b32 v128, v107, v128
	ds_bpermute_b32 v129, v107, v129
	ds_bpermute_b32 v130, v107, v130
	ds_bpermute_b32 v131, v107, v131
	s_waitcnt lgkmcnt(4)
	v_mfma_f32_16x16x32_bf16 v[10:13], v[124:127], v[0:3], v[10:13]
	s_nop 7
	v_pk_mul_f32 v[70:71], v[12:13], s[6:7] op_sel_hi:[1,0]
	v_pk_mul_f32 v[72:73], v[10:11], s[6:7] op_sel_hi:[1,0]
	v_mov_b32_e32 v78, v145
	s_nop 0
	v_mov_b32_e32 v79, v78
	v_mov_b32_e32 v80, v78
	v_mov_b32_e32 v81, v78
	s_nop 0
	s_waitcnt vmcnt(4)
	ds_bpermute_b32 v132, v107, v132
	ds_bpermute_b32 v133, v107, v133
	ds_bpermute_b32 v134, v107, v134
	ds_bpermute_b32 v135, v107, v135
	s_waitcnt lgkmcnt(4)
	v_mfma_f32_16x16x32_bf16 v[10:13], v[128:131], v[4:7], v[78:81]
	s_nop 2
	v_mov_b32_e32 v78, v145
	s_waitcnt vmcnt(3)
	ds_bpermute_b32 v136, v107, v136
	ds_bpermute_b32 v137, v107, v137
	ds_bpermute_b32 v138, v107, v138
	ds_bpermute_b32 v139, v107, v139
	s_waitcnt lgkmcnt(4)
	v_mfma_f32_16x16x32_bf16 v[10:13], v[132:135], v[0:3], v[10:13]
	s_nop 7
	v_pk_mul_f32 v[74:75], v[12:13], s[6:7] op_sel_hi:[1,0]
	v_pk_mul_f32 v[76:77], v[10:11], s[6:7] op_sel_hi:[1,0]
	s_nop 0
	v_mov_b32_e32 v79, v78
	v_mov_b32_e32 v80, v78
	v_mov_b32_e32 v81, v78
	s_nop 0
	s_waitcnt vmcnt(2)
	ds_bpermute_b32 v140, v107, v140
	ds_bpermute_b32 v141, v107, v141
	ds_bpermute_b32 v142, v107, v142
	ds_bpermute_b32 v143, v107, v143
	s_waitcnt lgkmcnt(4)
	v_mfma_f32_16x16x32_bf16 v[8:11], v[136:139], v[4:7], v[78:81]
	s_waitcnt vmcnt(1)
	ds_bpermute_b32 v148, v107, v148
	ds_bpermute_b32 v149, v107, v149
	ds_bpermute_b32 v150, v107, v150
	ds_bpermute_b32 v151, v107, v151
	s_waitcnt lgkmcnt(4)
	v_mfma_f32_16x16x32_bf16 v[8:11], v[140:143], v[0:3], v[8:11]
	s_nop 7
	v_pk_mul_f32 v[78:79], v[10:11], s[6:7] op_sel_hi:[1,0]
	v_pk_mul_f32 v[80:81], v[8:9], s[6:7] op_sel_hi:[1,0]
	v_mov_b32_e32 v84, v145
	s_nop 0
	v_mov_b32_e32 v85, v84
	v_mov_b32_e32 v86, v84
	v_mov_b32_e32 v87, v84
	s_nop 0
	s_waitcnt vmcnt(0)
	ds_bpermute_b32 v152, v107, v152
	ds_bpermute_b32 v153, v107, v153
	ds_bpermute_b32 v154, v107, v154
	ds_bpermute_b32 v155, v107, v155
	s_waitcnt lgkmcnt(4)
	v_mfma_f32_16x16x32_bf16 v[4:7], v[148:151], v[4:7], v[84:87]
	s_waitcnt lgkmcnt(0)
; __device__ __forceinline__ f32x4 mfma16(bf16x8 a, bf16x8 b, f32x4 c) { return __builtin_amdgcn_mfma_f32_16x16x32_bf16(a, b, c, 0, 0, 0); }
; __device__ __forceinline__ void mem_attn(const Params& p, int layer, int task) {
;     ...
;     acc = mfma16(a0, qf[0], acc); acc = mfma16(a1, qf[1], acc);
;     st[kb] = acc * 0.125f;
;   }
;   float mx = -3.0e38f;
; #pragma unroll
;   for (int kb = 0; kb < 16; kb++)
; #pragma unroll
;     for (int r = 0; r < 4; r++) mx = fmaxf(mx, st[kb][r]);
;   mx = fmaxf(mx, __shfl_xor(mx, 16)); mx = fmaxf(mx, __shfl_xor(mx, 32));
;   float sum = 0.f;
; #pragma unroll
;   for (int kb = 0; kb < 16; kb++)
; #pragma unroll
;     for (int r = 0; r < 4; r++) { float e = __expf(st[kb][r] - mx); st[kb][r] = e; sum += e; }
;   sum += __shfl_xor(sum, 16); sum += __shfl_xor(sum, 32);
	v_mfma_f32_16x16x32_bf16 v[2:5], v[152:155], v[0:3], v[4:7]
	s_setprio 0
	s_nop 5
	v_and_b32_e32 v6, 64, v202
	v_add_u32_e32 v7, 64, v6
	v_pk_mul_f32 v[0:1], v[4:5], s[6:7] op_sel_hi:[1,0]
	v_max3_f32 v4, v26, s0, v27
	v_max3_f32 v4, v4, v22, v23
	v_max3_f32 v4, v4, v28, v29
	v_max3_f32 v4, v4, v24, v25
	v_max3_f32 v4, v4, v36, v37
	v_max3_f32 v4, v4, v30, v31
	v_max3_f32 v4, v4, v38, v39
	v_max3_f32 v4, v4, v32, v33
	v_max3_f32 v4, v4, v42, v43
	v_max3_f32 v4, v4, v34, v35
	v_max3_f32 v4, v4, v44, v45
	v_max3_f32 v4, v4, v40, v41
	v_max3_f32 v4, v4, v50, v51
	v_max3_f32 v4, v4, v46, v47
	v_max3_f32 v4, v4, v52, v53
	v_max3_f32 v4, v4, v48, v49
	v_max3_f32 v4, v4, v58, v59
	v_max3_f32 v4, v4, v54, v55
	v_max3_f32 v4, v4, v60, v61
	v_max3_f32 v4, v4, v56, v57
	v_max3_f32 v4, v4, v66, v67
	v_max3_f32 v4, v4, v62, v63
	v_max3_f32 v4, v4, v68, v69
	v_max3_f32 v4, v4, v64, v65
	v_max3_f32 v4, v4, v72, v73
	v_max3_f32 v4, v4, v70, v71
	v_max3_f32 v4, v4, v76, v77
	v_max3_f32 v4, v4, v74, v75
	v_max3_f32 v4, v4, v80, v81
	v_xor_b32_e32 v5, 16, v202
	v_pk_mul_f32 v[2:3], v[2:3], s[6:7] op_sel_hi:[1,0]
	v_max3_f32 v4, v4, v78, v79
	v_cmp_lt_i32_e32 vcc, v5, v7
	v_max3_f32 v4, v4, v2, v3
	v_max3_f32 v4, v4, v0, v1
	v_cndmask_b32_e32 v5, v202, v5, vcc
	v_lshlrev_b32_e32 v6, 2, v5
	ds_bpermute_b32 v5, v6, v4
	s_mov_b64 s[0:1], 0xc0
	s_waitcnt lgkmcnt(0)
	v_max_f32_e32 v5, v5, v5
	v_max_f32_e32 v4, v4, v5
	v_xor_b32_e32 v5, 32, v202
	v_cmp_lt_i32_e32 vcc, v5, v7
	s_nop 1
	v_cndmask_b32_e32 v5, v202, v5, vcc
	v_lshlrev_b32_e32 v7, 2, v5
	ds_bpermute_b32 v5, v7, v4
	s_waitcnt lgkmcnt(0)
	v_max_f32_e32 v5, v5, v5
	v_max_f32_e32 v15, v4, v5
	v_sub_f32_e32 v9, v22, v15
	v_mul_f32_e32 v9, 0x3fb8aa3b, v9
	v_exp_f32_e32 v93, v9
	v_sub_f32_e32 v9, v23, v15
	v_mul_f32_e32 v9, 0x3fb8aa3b, v9
	v_exp_f32_e32 v95, v9
	v_sub_f32_e32 v9, v28, v15
	v_mul_f32_e32 v9, 0x3fb8aa3b, v9
	v_exp_f32_e32 v96, v9
	v_sub_f32_e32 v9, v29, v15
	v_mul_f32_e32 v9, 0x3fb8aa3b, v9
	v_exp_f32_e32 v99, v9
	v_sub_f32_e32 v9, v24, v15
	v_mul_f32_e32 v9, 0x3fb8aa3b, v9
	v_exp_f32_e32 v101, v9
	v_sub_f32_e32 v9, v25, v15
	v_mul_f32_e32 v9, 0x3fb8aa3b, v9
	v_exp_f32_e32 v103, v9
	v_sub_f32_e32 v9, v36, v15
	v_mul_f32_e32 v9, 0x3fb8aa3b, v9
	v_exp_f32_e32 v94, v9
	v_sub_f32_e32 v9, v37, v15
	v_mul_f32_e32 v9, 0x3fb8aa3b, v9
	v_exp_f32_e32 v97, v9
	v_sub_f32_e32 v9, v30, v15
	v_mul_f32_e32 v9, 0x3fb8aa3b, v9
	v_exp_f32_e32 v98, v9
	v_sub_f32_e32 v9, v31, v15
	v_mul_f32_e32 v9, 0x3fb8aa3b, v9
	v_exp_f32_e32 v100, v9
	v_sub_f32_e32 v9, v38, v15
	v_mul_f32_e32 v9, 0x3fb8aa3b, v9
	v_exp_f32_e32 v102, v9
	v_sub_f32_e32 v9, v39, v15
	v_mul_f32_e32 v9, 0x3fb8aa3b, v9
	v_exp_f32_e32 v104, v9
	v_sub_f32_e32 v9, v32, v15
	v_mul_f32_e32 v9, 0x3fb8aa3b, v9
	v_exp_f32_e32 v105, v9
	v_sub_f32_e32 v9, v33, v15
	v_mul_f32_e32 v9, 0x3fb8aa3b, v9
	v_exp_f32_e32 v106, v9
	v_sub_f32_e32 v9, v42, v15
	v_mul_f32_e32 v9, 0x3fb8aa3b, v9
	v_exp_f32_e32 v85, v9
	v_sub_f32_e32 v9, v43, v15
	v_mul_f32_e32 v9, 0x3fb8aa3b, v9
	v_exp_f32_e32 v86, v9
	v_sub_f32_e32 v9, v34, v15
	v_mul_f32_e32 v9, 0x3fb8aa3b, v9
	v_exp_f32_e32 v87, v9
	v_sub_f32_e32 v9, v35, v15
	v_mul_f32_e32 v9, 0x3fb8aa3b, v9
	v_exp_f32_e32 v88, v9
	v_sub_f32_e32 v9, v44, v15
	v_mul_f32_e32 v9, 0x3fb8aa3b, v9
	v_exp_f32_e32 v89, v9
	v_sub_f32_e32 v9, v45, v15
	v_mul_f32_e32 v9, 0x3fb8aa3b, v9
	v_exp_f32_e32 v90, v9
	v_sub_f32_e32 v9, v40, v15
	v_mul_f32_e32 v9, 0x3fb8aa3b, v9
	v_exp_f32_e32 v91, v9
	v_sub_f32_e32 v9, v41, v15
	v_mul_f32_e32 v9, 0x3fb8aa3b, v9
	v_exp_f32_e32 v92, v9
	v_sub_f32_e32 v9, v50, v15
	v_mul_f32_e32 v9, 0x3fb8aa3b, v9
	v_exp_f32_e32 v50, v9
	v_sub_f32_e32 v9, v51, v15
	v_mul_f32_e32 v9, 0x3fb8aa3b, v9
	v_exp_f32_e32 v51, v9
	v_sub_f32_e32 v9, v46, v15
	v_mul_f32_e32 v9, 0x3fb8aa3b, v9
	v_exp_f32_e32 v84, v9
	v_sub_f32_e32 v9, v47, v15
	v_sub_f32_e32 v4, v26, v15
	v_mul_f32_e32 v9, 0x3fb8aa3b, v9
	v_mul_f32_e32 v4, 0x3fb8aa3b, v4
	v_sub_f32_e32 v5, v27, v15
	v_exp_f32_e32 v47, v9
	v_sub_f32_e32 v9, v52, v15
	v_exp_f32_e32 v4, v4
	v_mul_f32_e32 v5, 0x3fb8aa3b, v5
	v_mul_f32_e32 v9, 0x3fb8aa3b, v9
	v_exp_f32_e32 v5, v5
	v_exp_f32_e32 v52, v9
	v_sub_f32_e32 v9, v53, v15
	v_mul_f32_e32 v9, 0x3fb8aa3b, v9
	v_exp_f32_e32 v53, v9
	v_sub_f32_e32 v9, v48, v15
	v_add_f32_e32 v8, 0, v4
	v_mul_f32_e32 v9, 0x3fb8aa3b, v9
	v_add_f32_e32 v8, v5, v8
	v_exp_f32_e32 v48, v9
	v_sub_f32_e32 v9, v49, v15
	v_add_f32_e32 v8, v93, v8
	v_mul_f32_e32 v9, 0x3fb8aa3b, v9
	v_add_f32_e32 v8, v95, v8
	v_exp_f32_e32 v49, v9
	v_sub_f32_e32 v9, v58, v15
	v_add_f32_e32 v8, v96, v8
	v_mul_f32_e32 v9, 0x3fb8aa3b, v9
	v_add_f32_e32 v8, v99, v8
	v_exp_f32_e32 v39, v9
	v_sub_f32_e32 v9, v59, v15
	v_add_f32_e32 v8, v101, v8
	v_mul_f32_e32 v9, 0x3fb8aa3b, v9
	v_add_f32_e32 v8, v103, v8
	v_exp_f32_e32 v40, v9
	v_sub_f32_e32 v9, v54, v15
	v_add_f32_e32 v8, v94, v8
	v_mul_f32_e32 v9, 0x3fb8aa3b, v9
	v_add_f32_e32 v8, v97, v8
	v_exp_f32_e32 v41, v9
	v_sub_f32_e32 v9, v55, v15
	v_add_f32_e32 v8, v98, v8
	v_mul_f32_e32 v9, 0x3fb8aa3b, v9
	v_add_f32_e32 v8, v100, v8
	v_exp_f32_e32 v42, v9
	v_sub_f32_e32 v9, v60, v15
	v_add_f32_e32 v8, v102, v8
	v_mul_f32_e32 v9, 0x3fb8aa3b, v9
	v_add_f32_e32 v8, v104, v8
	v_exp_f32_e32 v43, v9
	v_sub_f32_e32 v9, v61, v15
	v_add_f32_e32 v8, v105, v8
	v_mul_f32_e32 v9, 0x3fb8aa3b, v9
	v_add_f32_e32 v8, v106, v8
	v_exp_f32_e32 v44, v9
	v_sub_f32_e32 v9, v56, v15
	v_add_f32_e32 v8, v85, v8
	v_mul_f32_e32 v9, 0x3fb8aa3b, v9
	v_add_f32_e32 v8, v86, v8
	v_exp_f32_e32 v45, v9
	v_sub_f32_e32 v9, v57, v15
	v_add_f32_e32 v8, v87, v8
	v_mul_f32_e32 v9, 0x3fb8aa3b, v9
	v_add_f32_e32 v8, v88, v8
	v_exp_f32_e32 v46, v9
	v_sub_f32_e32 v9, v66, v15
; __device__ __forceinline__ float ozero() { float z = 0.f; asm volatile("" : "+v"(z)); return z; }
; __device__ __forceinline__ void mem_attn(const Params& p, int layer, int task) {
;     ...
;   float sum = 0.f;
; #pragma unroll
;   for (int kb = 0; kb < 16; kb++)
; #pragma unroll
;     for (int r = 0; r < 4; r++) { float e = __expf(st[kb][r] - mx); st[kb][r] = e; sum += e; }
;   sum += __shfl_xor(sum, 16); sum += __shfl_xor(sum, 32);
;   const float rinv = 1.f / sum;
;   f32x4 o[4];
; #pragma unroll
;   for (int mb = 0; mb < 4; mb++) { const float z_ = ozero(); o[mb] = (f32x4){z_, z_, z_, z_}; }
; #pragma unroll
;   for (int k2 = 0; k2 < 8; k2++) {
;     bf16x8 pf;
;     unsigned q0 = pk2(st[2 * k2][0], st[2 * k2][1]), q1 = pk2(st[2 * k2][2], st[2 * k2][3]);
;     unsigned q2 = pk2(st[2 * k2 + 1][0], st[2 * k2 + 1][1]), q3 = pk2(st[2 * k2 + 1][2], st[2 * k2 + 1][3]);
;     pf[0] = (short)(q0 & 0xFFFF); pf[1] = (short)(q0 >> 16); pf[2] = (short)(q1 & 0xFFFF); pf[3] = (short)(q1 >> 16);
;     pf[4] = (short)(q2 & 0xFFFF); pf[5] = (short)(q2 >> 16); pf[6] = (short)(q3 & 0xFFFF); pf[7] = (short)(q3 >> 16);
; #pragma unroll
;     for (int mb = 0; mb < 4; mb++) {
;       const bf* vp = mvt + (size_t)(16 * mb + n16) * 256 + 32 * k2 + 4 * kq;
;       uint2 v0 = *(const uint2*)vp, v1 = *(const uint2*)(vp + 16);
	v_add_f32_e32 v8, v89, v8
	v_mul_f32_e32 v9, 0x3fb8aa3b, v9
	v_add_f32_e32 v8, v90, v8
	v_exp_f32_e32 v31, v9
	v_sub_f32_e32 v9, v67, v15
	v_add_f32_e32 v8, v91, v8
	v_mul_f32_e32 v9, 0x3fb8aa3b, v9
	v_add_f32_e32 v8, v92, v8
	v_exp_f32_e32 v32, v9
	v_sub_f32_e32 v9, v62, v15
	v_add_f32_e32 v8, v50, v8
	v_mul_f32_e32 v9, 0x3fb8aa3b, v9
	v_add_f32_e32 v8, v51, v8
	v_exp_f32_e32 v33, v9
	v_sub_f32_e32 v9, v63, v15
	v_add_f32_e32 v8, v84, v8
	v_mul_f32_e32 v9, 0x3fb8aa3b, v9
	v_add_f32_e32 v8, v47, v8
	v_exp_f32_e32 v34, v9
	v_sub_f32_e32 v9, v68, v15
	v_add_f32_e32 v8, v52, v8
	v_mul_f32_e32 v9, 0x3fb8aa3b, v9
	v_add_f32_e32 v8, v53, v8
	v_exp_f32_e32 v35, v9
	v_sub_f32_e32 v9, v69, v15
	v_add_f32_e32 v8, v48, v8
	v_mul_f32_e32 v9, 0x3fb8aa3b, v9
	v_add_f32_e32 v8, v49, v8
	v_exp_f32_e32 v36, v9
	v_sub_f32_e32 v9, v64, v15
	v_add_f32_e32 v8, v39, v8
	v_mul_f32_e32 v9, 0x3fb8aa3b, v9
	v_add_f32_e32 v8, v40, v8
	v_exp_f32_e32 v37, v9
	v_sub_f32_e32 v9, v65, v15
	v_add_f32_e32 v8, v41, v8
	v_mul_f32_e32 v9, 0x3fb8aa3b, v9
	v_add_f32_e32 v8, v42, v8
	v_exp_f32_e32 v38, v9
	v_sub_f32_e32 v9, v72, v15
	v_add_f32_e32 v8, v43, v8
	v_mul_f32_e32 v9, 0x3fb8aa3b, v9
	v_add_f32_e32 v8, v44, v8
	v_exp_f32_e32 v23, v9
	v_sub_f32_e32 v9, v73, v15
	v_add_f32_e32 v8, v45, v8
	v_mul_f32_e32 v9, 0x3fb8aa3b, v9
	v_add_f32_e32 v8, v46, v8
	v_exp_f32_e32 v24, v9
	v_sub_f32_e32 v9, v70, v15
	v_add_f32_e32 v8, v31, v8
	v_mul_f32_e32 v9, 0x3fb8aa3b, v9
	v_add_f32_e32 v8, v32, v8
	v_exp_f32_e32 v25, v9
	v_sub_f32_e32 v9, v71, v15
	v_add_f32_e32 v8, v33, v8
	v_mul_f32_e32 v9, 0x3fb8aa3b, v9
	v_add_f32_e32 v8, v34, v8
	v_exp_f32_e32 v26, v9
	v_sub_f32_e32 v9, v76, v15
	v_add_f32_e32 v8, v35, v8
	v_mul_f32_e32 v9, 0x3fb8aa3b, v9
	v_add_f32_e32 v8, v36, v8
	v_exp_f32_e32 v27, v9
	v_sub_f32_e32 v9, v77, v15
	v_add_f32_e32 v8, v37, v8
	v_mul_f32_e32 v9, 0x3fb8aa3b, v9
	v_add_f32_e32 v8, v38, v8
	v_exp_f32_e32 v28, v9
	v_sub_f32_e32 v9, v74, v15
	v_add_f32_e32 v8, v23, v8
	v_mul_f32_e32 v9, 0x3fb8aa3b, v9
	v_add_f32_e32 v8, v24, v8
	v_exp_f32_e32 v29, v9
	v_sub_f32_e32 v9, v75, v15
	v_add_f32_e32 v8, v25, v8
	v_mul_f32_e32 v9, 0x3fb8aa3b, v9
	v_add_f32_e32 v8, v26, v8
	v_exp_f32_e32 v30, v9
	v_add_f32_e32 v8, v27, v8
	v_add_f32_e32 v8, v28, v8
	v_add_f32_e32 v8, v29, v8
	v_add_f32_e32 v9, v30, v8
	v_sub_f32_e32 v8, v80, v15
	v_mul_f32_e32 v8, 0x3fb8aa3b, v8
	v_exp_f32_e32 v8, v8
	v_sub_f32_e32 v2, v2, v15
	v_mul_f32_e32 v2, 0x3fb8aa3b, v2
	v_sub_f32_e32 v3, v3, v15
	v_add_f32_e32 v10, v8, v9
	v_sub_f32_e32 v9, v81, v15
	v_mul_f32_e32 v9, 0x3fb8aa3b, v9
	v_exp_f32_e32 v9, v9
	v_mul_f32_e32 v3, 0x3fb8aa3b, v3
	v_sub_f32_e32 v0, v0, v15
	v_mul_f32_e32 v0, 0x3fb8aa3b, v0
	v_add_f32_e32 v11, v9, v10
	v_sub_f32_e32 v10, v78, v15
	v_mul_f32_e32 v10, 0x3fb8aa3b, v10
	v_exp_f32_e32 v10, v10
	v_sub_f32_e32 v1, v1, v15
	v_exp_f32_e32 v14, v0
	v_mul_f32_e32 v1, 0x3fb8aa3b, v1
	v_add_f32_e32 v12, v10, v11
	v_sub_f32_e32 v11, v79, v15
	v_mul_f32_e32 v11, 0x3fb8aa3b, v11
	v_exp_f32_e32 v11, v11
	v_exp_f32_e32 v15, v1
	v_mov_b32_e32 v54, v145
	v_mov_b32_e32 v58, v145
	v_add_f32_e32 v13, v11, v12
	v_exp_f32_e32 v12, v2
	v_mov_b32_e32 v62, v145
	v_mov_b32_e32 v66, v145
	v_add_f32_e32 v2, v12, v13
	v_exp_f32_e32 v13, v3
	v_cvt_pk_bf16_f32 v70, v4, v5
	v_add_f32_e32 v2, v13, v2
	v_add_f32_e32 v0, v14, v2
	v_add_f32_e32 v0, v15, v0
	ds_bpermute_b32 v1, v6, v0
	v_mov_b32_e32 v55, v54
	v_mov_b32_e32 v56, v54
	v_mov_b32_e32 v57, v54
	v_cvt_pk_bf16_f32 v71, v93, v95
	s_waitcnt lgkmcnt(0)
	v_add_f32_e32 v0, v0, v1
	ds_bpermute_b32 v1, v7, v0
	v_cvt_pk_bf16_f32 v72, v96, v99
	v_cvt_pk_bf16_f32 v73, v101, v103
	v_mov_b32_e32 v59, v58
	v_mov_b32_e32 v60, v58
	s_waitcnt lgkmcnt(0)
	v_add_f32_e32 v22, v0, v1
	v_lshl_add_u64 v[0:1], s[8:9], 0, v[144:145]
	v_lshl_add_u64 v[6:7], v[0:1], 0, v[18:19]
	v_lshlrev_b32_e32 v144, 9, v83
	v_lshl_add_u64 v[0:1], v[6:7], 0, v[144:145]
	v_and_b32_e32 v146, 15, v202
	v_lshrrev_b32_e32 v147, 4, v202
	v_lshlrev_b32_e32 v146, 9, v146
	v_lshl_add_u32 v146, v147, 3, v146
	v_lshrrev_b32_e32 v147, 2, v202
	v_lshlrev_b32_e32 v147, 9, v147
	v_sub_u32_e32 v146, v147, v146
	v_and_b32_e32 v147, 3, v202
	v_lshl_add_u32 v146, v147, 3, v146
	v_ashrrev_i32_e32 v147, 31, v146
	v_lshl_add_u64 v[200:201], v[0:1], 0, v[146:147]
	v_mov_b32_e32 v198, 0x2000
	v_mov_b32_e32 v199, 0
	v_lshl_add_u64 v[146:147], v[200:201], 0, v[198:199]
	v_lshl_add_u64 v[196:197], v[146:147], 0, v[198:199]
	v_lshl_add_u64 v[198:199], v[196:197], 0, v[198:199]
	global_load_dwordx2 v[108:109], v[200:201], off
	global_load_dwordx2 v[110:111], v[200:201], off offset:32
	global_load_dwordx2 v[112:113], v[146:147], off
	global_load_dwordx2 v[114:115], v[146:147], off offset:32
	global_load_dwordx2 v[116:117], v[196:197], off
	global_load_dwordx2 v[118:119], v[196:197], off offset:32
	global_load_dwordx2 v[120:121], v[198:199], off
	global_load_dwordx2 v[122:123], v[198:199], off offset:32
	global_load_dwordx2 v[124:125], v[200:201], off offset:64
	global_load_dwordx2 v[126:127], v[200:201], off offset:96
	global_load_dwordx2 v[128:129], v[146:147], off offset:64
	global_load_dwordx2 v[130:131], v[146:147], off offset:96
	global_load_dwordx2 v[132:133], v[196:197], off offset:64
	global_load_dwordx2 v[134:135], v[196:197], off offset:96
	global_load_dwordx2 v[136:137], v[198:199], off offset:64
	global_load_dwordx2 v[138:139], v[198:199], off offset:96
	global_load_dwordx2 v[140:141], v[200:201], off offset:128
	global_load_dwordx2 v[142:143], v[200:201], off offset:160
	global_load_dwordx2 v[148:149], v[146:147], off offset:128
	global_load_dwordx2 v[150:151], v[146:147], off offset:160
; __device__ __forceinline__ f32x4 mfma16(bf16x8 a, bf16x8 b, f32x4 c) { return __builtin_amdgcn_mfma_f32_16x16x32_bf16(a, b, c, 0, 0, 0); }
; __device__ __forceinline__ void mem_attn(const Params& p, int layer, int task) {
;     ...
;   for (int k2 = 0; k2 < 8; k2++) {
;     bf16x8 pf;
;     unsigned q0 = pk2(st[2 * k2][0], st[2 * k2][1]), q1 = pk2(st[2 * k2][2], st[2 * k2][3]);
;     unsigned q2 = pk2(st[2 * k2 + 1][0], st[2 * k2 + 1][1]), q3 = pk2(st[2 * k2 + 1][2], st[2 * k2 + 1][3]);
;     pf[0] = (short)(q0 & 0xFFFF); pf[1] = (short)(q0 >> 16); pf[2] = (short)(q1 & 0xFFFF); pf[3] = (short)(q1 >> 16);
;     pf[4] = (short)(q2 & 0xFFFF); pf[5] = (short)(q2 >> 16); pf[6] = (short)(q3 & 0xFFFF); pf[7] = (short)(q3 >> 16);
; #pragma unroll
;     for (int mb = 0; mb < 4; mb++) {
;       const bf* vp = mvt + (size_t)(16 * mb + n16) * 256 + 32 * k2 + 4 * kq;
;       uint2 v0 = *(const uint2*)vp, v1 = *(const uint2*)(vp + 16);
;       bf16x8 af;
;       af[0] = (short)(v0.x & 0xFFFF); af[1] = (short)(v0.x >> 16); af[2] = (short)(v0.y & 0xFFFF); af[3] = (short)(v0.y >> 16);
;       af[4] = (short)(v1.x & 0xFFFF); af[5] = (short)(v1.x >> 16); af[6] = (short)(v1.y & 0xFFFF); af[7] = (short)(v1.y >> 16);
;       o[mb] = mfma16(af, pf, o[mb]);
	global_load_dwordx2 v[152:153], v[196:197], off offset:128
	global_load_dwordx2 v[154:155], v[196:197], off offset:160
	global_load_dwordx2 v[156:157], v[198:199], off offset:128
	global_load_dwordx2 v[158:159], v[198:199], off offset:160
	global_load_dwordx2 v[160:161], v[200:201], off offset:192
	global_load_dwordx2 v[162:163], v[200:201], off offset:224
	global_load_dwordx2 v[164:165], v[146:147], off offset:192
	global_load_dwordx2 v[166:167], v[146:147], off offset:224
	global_load_dwordx2 v[168:169], v[196:197], off offset:192
	global_load_dwordx2 v[170:171], v[196:197], off offset:224
	global_load_dwordx2 v[172:173], v[198:199], off offset:192
	global_load_dwordx2 v[174:175], v[198:199], off offset:224
	global_load_dwordx2 v[176:177], v[200:201], off offset:256
	global_load_dwordx2 v[178:179], v[200:201], off offset:288
	global_load_dwordx2 v[180:181], v[146:147], off offset:256
	global_load_dwordx2 v[182:183], v[146:147], off offset:288
	global_load_dwordx2 v[184:185], v[196:197], off offset:256
	global_load_dwordx2 v[186:187], v[196:197], off offset:288
	global_load_dwordx2 v[188:189], v[198:199], off offset:256
	global_load_dwordx2 v[190:191], v[198:199], off offset:288
	global_load_dwordx2 v[192:193], v[200:201], off offset:320
	global_load_dwordx2 v[194:195], v[200:201], off offset:352
	v_mov_b32_e32 v61, v58
	v_mov_b32_e32 v63, v62
	v_mov_b32_e32 v64, v62
	v_mov_b32_e32 v65, v62
	v_mov_b32_e32 v67, v66
	v_mov_b32_e32 v68, v66
	v_mov_b32_e32 v69, v66
	v_lshl_add_u64 v[78:79], v[6:7], 0, 64
	v_cvt_pk_bf16_f32 v50, v50, v51
	v_cvt_pk_bf16_f32 v51, v84, v47
	v_cvt_pk_bf16_f32 v52, v52, v53
	v_cvt_pk_bf16_f32 v53, v48, v49
	v_lshl_add_u64 v[48:49], v[6:7], 0, s[0:1]
	v_cvt_pk_bf16_f32 v41, v41, v42
	v_cvt_pk_bf16_f32 v42, v43, v44
	v_cvt_pk_bf16_f32 v43, v45, v46
	v_cvt_pk_bf16_f32 v40, v39, v40
	v_cvt_pk_bf16_f32 v33, v33, v34
	v_cvt_pk_bf16_f32 v34, v35, v36
	v_cvt_pk_bf16_f32 v35, v37, v38
	s_mov_b64 s[0:1], 0x140
	v_cvt_pk_bf16_f32 v32, v31, v32
	v_cvt_pk_bf16_f32 v25, v25, v26
	v_cvt_pk_bf16_f32 v26, v27, v28
	v_cvt_pk_bf16_f32 v27, v29, v30
	v_cvt_pk_bf16_f32 v24, v23, v24
	s_nop 0
	s_nop 1
	s_waitcnt vmcnt(40)
	ds_bpermute_b32 v108, v107, v108
	ds_bpermute_b32 v109, v107, v109
	ds_bpermute_b32 v110, v107, v110
	ds_bpermute_b32 v111, v107, v111
	s_waitcnt vmcnt(38)
	ds_bpermute_b32 v112, v107, v112
	ds_bpermute_b32 v113, v107, v113
	ds_bpermute_b32 v114, v107, v114
	ds_bpermute_b32 v115, v107, v115
	s_waitcnt lgkmcnt(4)
	s_setprio 1
	v_mfma_f32_16x16x32_bf16 v[54:57], v[108:111], v[70:73], v[54:57]
	global_load_dwordx2 v[108:109], v[146:147], off offset:320
	global_load_dwordx2 v[110:111], v[146:147], off offset:352
	v_or_b32_e32 v2, 0x2000, v144
	v_mov_b32_e32 v3, v145
	v_lshl_add_u64 v[4:5], v[6:7], 0, v[2:3]
	v_or_b32_e32 v4, 0x4000, v144
	v_mov_b32_e32 v5, v145
	v_or_b32_e32 v144, 0x6000, v144
	s_nop 0
	s_nop 1
	s_waitcnt vmcnt(38)
	ds_bpermute_b32 v116, v107, v116
	ds_bpermute_b32 v117, v107, v117
	ds_bpermute_b32 v118, v107, v118
	ds_bpermute_b32 v119, v107, v119
	s_waitcnt lgkmcnt(4)
	v_mfma_f32_16x16x32_bf16 v[58:61], v[112:115], v[70:73], v[58:61]
	global_load_dwordx2 v[112:113], v[196:197], off offset:320
	global_load_dwordx2 v[114:115], v[196:197], off offset:352
	v_lshl_add_u64 v[76:77], v[6:7], 0, v[4:5]
	s_nop 0
	s_nop 0
	s_nop 1
	s_waitcnt vmcnt(38)
	ds_bpermute_b32 v120, v107, v120
	ds_bpermute_b32 v121, v107, v121
	ds_bpermute_b32 v122, v107, v122
	ds_bpermute_b32 v123, v107, v123
	s_waitcnt lgkmcnt(4)
	v_mfma_f32_16x16x32_bf16 v[62:65], v[116:119], v[70:73], v[62:65]
	global_load_dwordx2 v[116:117], v[198:199], off offset:320
	global_load_dwordx2 v[118:119], v[198:199], off offset:352
	v_lshl_add_u64 v[76:77], v[6:7], 0, v[144:145]
	s_nop 0
	s_nop 0
	s_nop 1
	s_waitcnt vmcnt(38)
	ds_bpermute_b32 v124, v107, v124
	ds_bpermute_b32 v125, v107, v125
	ds_bpermute_b32 v126, v107, v126
	ds_bpermute_b32 v127, v107, v127
	s_waitcnt lgkmcnt(4)
	v_mfma_f32_16x16x32_bf16 v[66:69], v[120:123], v[70:73], v[66:69]
	global_load_dwordx2 v[120:121], v[200:201], off offset:384
	global_load_dwordx2 v[122:123], v[200:201], off offset:416
	v_cvt_pk_bf16_f32 v70, v94, v97
	v_cvt_pk_bf16_f32 v71, v98, v100
	v_cvt_pk_bf16_f32 v72, v102, v104
	v_cvt_pk_bf16_f32 v73, v105, v106
	s_nop 0
	s_nop 1
	s_waitcnt vmcnt(38)
	ds_bpermute_b32 v128, v107, v128
	ds_bpermute_b32 v129, v107, v129
	ds_bpermute_b32 v130, v107, v130
	ds_bpermute_b32 v131, v107, v131
	s_waitcnt lgkmcnt(4)
	v_mfma_f32_16x16x32_bf16 v[54:57], v[124:127], v[70:73], v[54:57]
	global_load_dwordx2 v[124:125], v[146:147], off offset:384
	global_load_dwordx2 v[126:127], v[146:147], off offset:416
	v_lshl_add_u64 v[76:77], v[78:79], 0, v[2:3]
	s_nop 0
	s_nop 0
	s_nop 1
	s_waitcnt vmcnt(38)
	ds_bpermute_b32 v132, v107, v132
	ds_bpermute_b32 v133, v107, v133
	ds_bpermute_b32 v134, v107, v134
	ds_bpermute_b32 v135, v107, v135
	s_waitcnt lgkmcnt(4)
	v_mfma_f32_16x16x32_bf16 v[58:61], v[128:131], v[70:73], v[58:61]
	global_load_dwordx2 v[128:129], v[196:197], off offset:384
	global_load_dwordx2 v[130:131], v[196:197], off offset:416
	v_lshl_add_u64 v[76:77], v[78:79], 0, v[4:5]
	s_nop 0
	s_nop 0
	s_nop 1
	s_waitcnt vmcnt(38)
	ds_bpermute_b32 v136, v107, v136
	ds_bpermute_b32 v137, v107, v137
	ds_bpermute_b32 v138, v107, v138
	ds_bpermute_b32 v139, v107, v139
	s_waitcnt lgkmcnt(4)
	v_mfma_f32_16x16x32_bf16 v[62:65], v[132:135], v[70:73], v[62:65]
	global_load_dwordx2 v[132:133], v[198:199], off offset:384
	global_load_dwordx2 v[134:135], v[198:199], off offset:416
	v_lshl_add_u64 v[76:77], v[78:79], 0, v[144:145]
	s_nop 0
	v_lshl_add_u64 v[78:79], v[6:7], 0, s[50:51]
	s_nop 0
	s_nop 1
	s_waitcnt vmcnt(38)
; __device__ __forceinline__ f32x4 mfma16(bf16x8 a, bf16x8 b, f32x4 c) { return __builtin_amdgcn_mfma_f32_16x16x32_bf16(a, b, c, 0, 0, 0); }
; __device__ __forceinline__ void mem_attn(const Params& p, int layer, int task) {
;     ...
;   for (int k2 = 0; k2 < 8; k2++) {
;     bf16x8 pf;
;     unsigned q0 = pk2(st[2 * k2][0], st[2 * k2][1]), q1 = pk2(st[2 * k2][2], st[2 * k2][3]);
;     unsigned q2 = pk2(st[2 * k2 + 1][0], st[2 * k2 + 1][1]), q3 = pk2(st[2 * k2 + 1][2], st[2 * k2 + 1][3]);
;     pf[0] = (short)(q0 & 0xFFFF); pf[1] = (short)(q0 >> 16); pf[2] = (short)(q1 & 0xFFFF); pf[3] = (short)(q1 >> 16);
;     pf[4] = (short)(q2 & 0xFFFF); pf[5] = (short)(q2 >> 16); pf[6] = (short)(q3 & 0xFFFF); pf[7] = (short)(q3 >> 16);
; #pragma unroll
;     for (int mb = 0; mb < 4; mb++) {
;       const bf* vp = mvt + (size_t)(16 * mb + n16) * 256 + 32 * k2 + 4 * kq;
;       uint2 v0 = *(const uint2*)vp, v1 = *(const uint2*)(vp + 16);
;       bf16x8 af;
;       af[0] = (short)(v0.x & 0xFFFF); af[1] = (short)(v0.x >> 16); af[2] = (short)(v0.y & 0xFFFF); af[3] = (short)(v0.y >> 16);
;       af[4] = (short)(v1.x & 0xFFFF); af[5] = (short)(v1.x >> 16); af[6] = (short)(v1.y & 0xFFFF); af[7] = (short)(v1.y >> 16);
;       o[mb] = mfma16(af, pf, o[mb]);
	ds_bpermute_b32 v140, v107, v140
	ds_bpermute_b32 v141, v107, v141
	ds_bpermute_b32 v142, v107, v142
	ds_bpermute_b32 v143, v107, v143
	s_waitcnt lgkmcnt(4)
	v_mfma_f32_16x16x32_bf16 v[66:69], v[136:139], v[70:73], v[66:69]
	global_load_dwordx2 v[136:137], v[200:201], off offset:448
	global_load_dwordx2 v[138:139], v[200:201], off offset:480
	v_cvt_pk_bf16_f32 v70, v85, v86
	v_cvt_pk_bf16_f32 v71, v87, v88
	v_cvt_pk_bf16_f32 v72, v89, v90
	v_cvt_pk_bf16_f32 v73, v91, v92
	s_nop 0
	s_nop 1
	s_waitcnt vmcnt(38)
	ds_bpermute_b32 v148, v107, v148
	ds_bpermute_b32 v149, v107, v149
	ds_bpermute_b32 v150, v107, v150
	ds_bpermute_b32 v151, v107, v151
	s_waitcnt lgkmcnt(4)
	v_mfma_f32_16x16x32_bf16 v[54:57], v[140:143], v[70:73], v[54:57]
	global_load_dwordx2 v[140:141], v[146:147], off offset:448
	global_load_dwordx2 v[142:143], v[146:147], off offset:480
	v_lshl_add_u64 v[76:77], v[78:79], 0, v[2:3]
	s_nop 0
	s_nop 0
	s_nop 1
	s_waitcnt vmcnt(38)
	ds_bpermute_b32 v152, v107, v152
	ds_bpermute_b32 v153, v107, v153
	ds_bpermute_b32 v154, v107, v154
	ds_bpermute_b32 v155, v107, v155
	s_waitcnt lgkmcnt(4)
	v_mfma_f32_16x16x32_bf16 v[58:61], v[148:151], v[70:73], v[58:61]
	global_load_dwordx2 v[148:149], v[196:197], off offset:448
	global_load_dwordx2 v[150:151], v[196:197], off offset:480
	v_lshl_add_u64 v[76:77], v[78:79], 0, v[4:5]
	s_nop 0
	s_nop 0
	s_nop 1
	s_waitcnt vmcnt(38)
	ds_bpermute_b32 v156, v107, v156
	ds_bpermute_b32 v157, v107, v157
	ds_bpermute_b32 v158, v107, v158
	ds_bpermute_b32 v159, v107, v159
	s_waitcnt lgkmcnt(4)
	v_mfma_f32_16x16x32_bf16 v[62:65], v[152:155], v[70:73], v[62:65]
	global_load_dwordx2 v[152:153], v[198:199], off offset:448
	global_load_dwordx2 v[154:155], v[198:199], off offset:480
	v_lshl_add_u64 v[76:77], v[78:79], 0, v[144:145]
	s_nop 0
	s_nop 0
	s_nop 1
	s_waitcnt vmcnt(38)
	ds_bpermute_b32 v160, v107, v160
	ds_bpermute_b32 v161, v107, v161
	ds_bpermute_b32 v162, v107, v162
	ds_bpermute_b32 v163, v107, v163
	s_waitcnt lgkmcnt(4)
	v_mfma_f32_16x16x32_bf16 v[66:69], v[156:159], v[70:73], v[66:69]
	s_nop 0
	s_nop 1
	s_waitcnt vmcnt(36)
	ds_bpermute_b32 v164, v107, v164
	ds_bpermute_b32 v165, v107, v165
	ds_bpermute_b32 v166, v107, v166
	ds_bpermute_b32 v167, v107, v167
	s_waitcnt lgkmcnt(4)
	v_mfma_f32_16x16x32_bf16 v[54:57], v[160:163], v[50:53], v[54:57]
	v_lshl_add_u64 v[72:73], v[48:49], 0, v[2:3]
	s_nop 0
	s_nop 0
	s_nop 1
	s_waitcnt vmcnt(34)
	ds_bpermute_b32 v168, v107, v168
	ds_bpermute_b32 v169, v107, v169
	ds_bpermute_b32 v170, v107, v170
	ds_bpermute_b32 v171, v107, v171
	s_waitcnt lgkmcnt(4)
	v_mfma_f32_16x16x32_bf16 v[58:61], v[164:167], v[50:53], v[58:61]
	v_lshl_add_u64 v[72:73], v[48:49], 0, v[4:5]
	s_nop 0
	v_lshl_add_u64 v[48:49], v[48:49], 0, v[144:145]
	s_nop 0
	s_nop 1
	s_waitcnt vmcnt(32)
	ds_bpermute_b32 v172, v107, v172
	ds_bpermute_b32 v173, v107, v173
	ds_bpermute_b32 v174, v107, v174
	ds_bpermute_b32 v175, v107, v175
	s_waitcnt lgkmcnt(4)
	v_mfma_f32_16x16x32_bf16 v[62:65], v[168:171], v[50:53], v[62:65]
	s_nop 0
	s_nop 0
	s_waitcnt vmcnt(30)
	ds_bpermute_b32 v176, v107, v176
	ds_bpermute_b32 v177, v107, v177
	ds_bpermute_b32 v178, v107, v178
	ds_bpermute_b32 v179, v107, v179
	s_waitcnt lgkmcnt(4)
	v_mfma_f32_16x16x32_bf16 v[48:51], v[172:175], v[50:53], v[66:69]
	s_nop 2
	v_lshl_add_u64 v[66:67], v[6:7], 0, s[70:71]
	s_waitcnt vmcnt(28)
	ds_bpermute_b32 v180, v107, v180
	ds_bpermute_b32 v181, v107, v181
	ds_bpermute_b32 v182, v107, v182
	ds_bpermute_b32 v183, v107, v183
	s_waitcnt lgkmcnt(4)
	v_mfma_f32_16x16x32_bf16 v[44:47], v[176:179], v[40:43], v[54:57]
	s_nop 2
	v_lshl_add_u64 v[54:55], v[66:67], 0, v[2:3]
	s_nop 0
	s_nop 0
	s_nop 1
	s_waitcnt vmcnt(26)
	ds_bpermute_b32 v184, v107, v184
	ds_bpermute_b32 v185, v107, v185
	ds_bpermute_b32 v186, v107, v186
	ds_bpermute_b32 v187, v107, v187
	s_waitcnt lgkmcnt(4)
	v_mfma_f32_16x16x32_bf16 v[52:55], v[180:183], v[40:43], v[58:61]
	s_nop 2
	v_lshl_add_u64 v[58:59], v[66:67], 0, v[4:5]
	s_nop 0
	s_nop 0
	s_nop 1
	s_waitcnt vmcnt(24)
	ds_bpermute_b32 v188, v107, v188
	ds_bpermute_b32 v189, v107, v189
	ds_bpermute_b32 v190, v107, v190
	ds_bpermute_b32 v191, v107, v191
	s_waitcnt lgkmcnt(4)
	v_mfma_f32_16x16x32_bf16 v[56:59], v[184:187], v[40:43], v[62:65]
	s_nop 2
	v_lshl_add_u64 v[62:63], v[66:67], 0, v[144:145]
	s_nop 0
	s_nop 0
	s_nop 0
	s_nop 0
	s_waitcnt vmcnt(22)
	ds_bpermute_b32 v192, v107, v192
	ds_bpermute_b32 v193, v107, v193
	ds_bpermute_b32 v194, v107, v194
	ds_bpermute_b32 v195, v107, v195
	s_waitcnt lgkmcnt(4)
	v_mfma_f32_16x16x32_bf16 v[40:43], v[188:191], v[40:43], v[48:51]
	v_lshl_add_u64 v[60:61], v[6:7], 0, s[0:1]
	s_nop 1
	v_lshl_add_u64 v[50:51], v[60:61], 0, v[4:5]
	s_mov_b64 s[0:1], 0x1c0
	s_waitcnt vmcnt(20)
	ds_bpermute_b32 v108, v107, v108
	ds_bpermute_b32 v109, v107, v109
	ds_bpermute_b32 v110, v107, v110
	ds_bpermute_b32 v111, v107, v111
	s_waitcnt lgkmcnt(4)
	v_mfma_f32_16x16x32_bf16 v[36:39], v[192:195], v[32:35], v[44:47]
	s_nop 2
	v_lshl_add_u64 v[46:47], v[60:61], 0, v[2:3]
	s_nop 0
	s_nop 0
	s_nop 0
	s_nop 0
	s_nop 1
	s_waitcnt vmcnt(18)
	ds_bpermute_b32 v112, v107, v112
	ds_bpermute_b32 v113, v107, v113
	ds_bpermute_b32 v114, v107, v114
	ds_bpermute_b32 v115, v107, v115
	s_waitcnt lgkmcnt(4)
	v_mfma_f32_16x16x32_bf16 v[44:47], v[108:111], v[32:35], v[52:55]
	s_nop 2
	v_lshl_add_u64 v[54:55], v[60:61], 0, v[144:145]
	s_nop 0
	s_nop 0
	s_nop 0
	s_nop 0
	s_nop 0
	s_waitcnt vmcnt(16)
	ds_bpermute_b32 v116, v107, v116
	ds_bpermute_b32 v117, v107, v117
	ds_bpermute_b32 v118, v107, v118
	ds_bpermute_b32 v119, v107, v119
	s_waitcnt lgkmcnt(4)
	v_mfma_f32_16x16x32_bf16 v[48:51], v[112:115], v[32:35], v[56:59]
	s_waitcnt vmcnt(14)
; __device__ __forceinline__ float bflo(unsigned u) { return __uint_as_float(u << 16); }
; __device__ __forceinline__ float bfhi(unsigned u) { return __uint_as_float(u & 0xFFFF0000u); }
; __device__ __forceinline__ float siluf_(float x) { return x * __builtin_amdgcn_rcpf(1.f + __expf(-x)); }
; __device__ __forceinline__ f32x4 mfma16(bf16x8 a, bf16x8 b, f32x4 c) { return __builtin_amdgcn_mfma_f32_16x16x32_bf16(a, b, c, 0, 0, 0); }
; __device__ __forceinline__ void mem_attn(const Params& p, int layer, int task) {
;     ...
;   for (int k2 = 0; k2 < 8; k2++) {
;     bf16x8 pf;
;     unsigned q0 = pk2(st[2 * k2][0], st[2 * k2][1]), q1 = pk2(st[2 * k2][2], st[2 * k2][3]);
;     unsigned q2 = pk2(st[2 * k2 + 1][0], st[2 * k2 + 1][1]), q3 = pk2(st[2 * k2 + 1][2], st[2 * k2 + 1][3]);
;     pf[0] = (short)(q0 & 0xFFFF); pf[1] = (short)(q0 >> 16); pf[2] = (short)(q1 & 0xFFFF); pf[3] = (short)(q1 >> 16);
;     pf[4] = (short)(q2 & 0xFFFF); pf[5] = (short)(q2 >> 16); pf[6] = (short)(q3 & 0xFFFF); pf[7] = (short)(q3 >> 16);
; #pragma unroll
;     for (int mb = 0; mb < 4; mb++) {
;       const bf* vp = mvt + (size_t)(16 * mb + n16) * 256 + 32 * k2 + 4 * kq;
;       uint2 v0 = *(const uint2*)vp, v1 = *(const uint2*)(vp + 16);
;       bf16x8 af;
;       af[0] = (short)(v0.x & 0xFFFF); af[1] = (short)(v0.x >> 16); af[2] = (short)(v0.y & 0xFFFF); af[3] = (short)(v0.y >> 16);
;       af[4] = (short)(v1.x & 0xFFFF); af[5] = (short)(v1.x >> 16); af[6] = (short)(v1.y & 0xFFFF); af[7] = (short)(v1.y >> 16);
;       o[mb] = mfma16(af, pf, o[mb]);
;     }
;   }
;   const size_t tok = tok0 + n16;
; #pragma unroll
;   for (int mb = 0; mb < 4; mb++) {
;     const int d = 16 * mb + 4 * kq;
;     uint2 zz = *(const uint2*)(p.P + tok * PW + C_MEZ + h * 64 + d);
;     float v0 = o[mb][0] * rinv * siluf_(bflo(zz.x)), v1 = o[mb][1] * rinv * siluf_(bfhi(zz.x));
;     float v2 = o[mb][2] * rinv * siluf_(bflo(zz.y)), v3 = o[mb][3] * rinv * siluf_(bfhi(zz.y));
	ds_bpermute_b32 v120, v107, v120
	ds_bpermute_b32 v121, v107, v121
	ds_bpermute_b32 v122, v107, v122
	ds_bpermute_b32 v123, v107, v123
	s_waitcnt lgkmcnt(4)
	v_mfma_f32_16x16x32_bf16 v[32:35], v[116:119], v[32:35], v[40:43]
	v_lshl_add_u64 v[52:53], v[6:7], 0, s[72:73]
	s_waitcnt vmcnt(12)
	ds_bpermute_b32 v124, v107, v124
	ds_bpermute_b32 v125, v107, v125
	ds_bpermute_b32 v126, v107, v126
	ds_bpermute_b32 v127, v107, v127
	s_waitcnt lgkmcnt(4)
	v_mfma_f32_16x16x32_bf16 v[28:31], v[120:123], v[24:27], v[36:39]
	s_nop 0
	v_lshl_add_u64 v[42:43], v[52:53], 0, v[4:5]
	s_nop 0
	v_lshl_add_u64 v[38:39], v[52:53], 0, v[2:3]
	s_nop 0
	s_nop 0
	s_nop 0
	s_nop 0
	s_nop 1
	s_waitcnt vmcnt(10)
	ds_bpermute_b32 v128, v107, v128
	ds_bpermute_b32 v129, v107, v129
	ds_bpermute_b32 v130, v107, v130
	ds_bpermute_b32 v131, v107, v131
	s_waitcnt lgkmcnt(4)
	v_mfma_f32_16x16x32_bf16 v[36:39], v[124:127], v[24:27], v[44:47]
	s_nop 2
	v_lshl_add_u64 v[46:47], v[52:53], 0, v[144:145]
	s_nop 0
	s_nop 0
	s_nop 0
	s_waitcnt vmcnt(8)
	ds_bpermute_b32 v132, v107, v132
	ds_bpermute_b32 v133, v107, v133
	ds_bpermute_b32 v134, v107, v134
	ds_bpermute_b32 v135, v107, v135
	s_waitcnt lgkmcnt(4)
	v_mfma_f32_16x16x32_bf16 v[40:43], v[128:131], v[24:27], v[48:51]
	s_nop 0
	s_waitcnt vmcnt(6)
	ds_bpermute_b32 v136, v107, v136
	ds_bpermute_b32 v137, v107, v137
	ds_bpermute_b32 v138, v107, v138
	ds_bpermute_b32 v139, v107, v139
	s_waitcnt lgkmcnt(4)
	v_mfma_f32_16x16x32_bf16 v[24:27], v[132:135], v[24:27], v[32:35]
	v_lshl_add_u64 v[44:45], v[6:7], 0, s[0:1]
	v_lshl_add_u64 v[2:3], v[44:45], 0, v[2:3]
	v_div_scale_f32 v23, s[0:1], v22, v22, 1.0
	v_cvt_pk_bf16_f32 v32, v8, v9
	s_nop 0
	s_nop 0
	v_cvt_pk_bf16_f32 v33, v10, v11
	v_cvt_pk_bf16_f32 v34, v12, v13
	v_cvt_pk_bf16_f32 v35, v14, v15
	s_mov_b64 s[0:1], 0x2ac0
	s_nop 0
	s_nop 0
	s_waitcnt vmcnt(4)
	ds_bpermute_b32 v140, v107, v140
	ds_bpermute_b32 v141, v107, v141
	ds_bpermute_b32 v142, v107, v142
	ds_bpermute_b32 v143, v107, v143
	s_waitcnt lgkmcnt(4)
	v_mfma_f32_16x16x32_bf16 v[12:15], v[136:139], v[32:35], v[28:31]
	s_nop 0
	s_waitcnt vmcnt(2)
	ds_bpermute_b32 v148, v107, v148
	ds_bpermute_b32 v149, v107, v149
	ds_bpermute_b32 v150, v107, v150
	ds_bpermute_b32 v151, v107, v151
	s_waitcnt lgkmcnt(4)
	v_mfma_f32_16x16x32_bf16 v[8:11], v[140:143], v[32:35], v[36:39]
	v_lshl_add_u64 v[2:3], v[44:45], 0, v[4:5]
	s_nop 0
	s_nop 0
	s_nop 1
	s_waitcnt vmcnt(0)
	ds_bpermute_b32 v152, v107, v152
	ds_bpermute_b32 v153, v107, v153
	ds_bpermute_b32 v154, v107, v154
	ds_bpermute_b32 v155, v107, v155
	s_waitcnt lgkmcnt(4)
	v_mfma_f32_16x16x32_bf16 v[4:7], v[148:151], v[32:35], v[40:43]
	v_lshl_add_u64 v[2:3], v[44:45], 0, v[144:145]
	s_nop 0
	s_nop 0
	s_nop 1
	s_waitcnt lgkmcnt(0)
	v_mfma_f32_16x16x32_bf16 v[0:3], v[152:155], v[32:35], v[24:27]
	s_setprio 0
	s_nop 2
	v_rcp_f32_e32 v24, v23
	s_nop 0
	v_fma_f32 v25, -v23, v24, 1.0
	v_fmac_f32_e32 v24, v25, v24
	v_div_scale_f32 v25, vcc, 1.0, v22, 1.0
	v_mul_f32_e32 v26, v25, v24
	v_fma_f32 v27, -v23, v26, v25
	v_fmac_f32_e32 v26, v27, v24
	v_fma_f32 v23, -v23, v26, v25
	v_div_fmas_f32 v23, v23, v24, v26
	v_lshl_add_u64 v[24:25], v[20:21], 0, v[18:19]
	v_lshl_add_u64 v[20:21], v[24:25], 0, s[0:1]
	v_add_co_u32_e32 v24, vcc, s2, v24
	v_div_fixup_f32 v22, v23, v22, 1.0
	s_nop 0
	v_addc_co_u32_e32 v25, vcc, 0, v25, vcc
	global_load_dwordx2 v[24:25], v[24:25], off offset:2752
	s_waitcnt vmcnt(0)
; __device__ __forceinline__ float bflo(unsigned u) { return __uint_as_float(u << 16); }
; __device__ __forceinline__ float bfhi(unsigned u) { return __uint_as_float(u & 0xFFFF0000u); }
; __device__ __forceinline__ float siluf_(float x) { return x * __builtin_amdgcn_rcpf(1.f + __expf(-x)); }
; __device__ __forceinline__ void mem_attn(const Params& p, int layer, int task) {
;     ...
;   const size_t tok = tok0 + n16;
; #pragma unroll
;   for (int mb = 0; mb < 4; mb++) {
;     const int d = 16 * mb + 4 * kq;
;     uint2 zz = *(const uint2*)(p.P + tok * PW + C_MEZ + h * 64 + d);
;     float v0 = o[mb][0] * rinv * siluf_(bflo(zz.x)), v1 = o[mb][1] * rinv * siluf_(bfhi(zz.x));
;     float v2 = o[mb][2] * rinv * siluf_(bflo(zz.y)), v3 = o[mb][3] * rinv * siluf_(bfhi(zz.y));
;     *(uint2*)(p.Y + tok * YW + Y_MEM + h * 64 + d) = make_uint2(pk2(v0, v1), pk2(v2, v3));
;   }
	v_lshlrev_b32_e32 v26, 16, v24
	v_mul_f32_e32 v23, 0xbfb8aa3b, v26
	v_exp_f32_e32 v23, v23
	v_and_b32_e32 v27, 0xffff0000, v24
	v_lshlrev_b32_e32 v24, 16, v25
	v_and_b32_e32 v25, 0xffff0000, v25
	v_add_f32_e32 v23, 1.0, v23
	v_rcp_f32_e32 v28, v23
	v_pk_mul_f32 v[12:13], v[22:23], v[12:13] op_sel_hi:[0,1]
	v_mul_f32_e32 v23, 0xbfb8aa3b, v27
	v_exp_f32_e32 v23, v23
	s_nop 0
	v_add_f32_e32 v23, 1.0, v23
	v_rcp_f32_e32 v29, v23
	v_mul_f32_e32 v23, 0xbfb8aa3b, v24
	v_exp_f32_e32 v23, v23
	v_pk_mul_f32 v[26:27], v[28:29], v[26:27]
	s_nop 0
	v_pk_mul_f32 v[12:13], v[12:13], v[26:27]
	v_add_f32_e32 v23, 1.0, v23
	v_rcp_f32_e32 v26, v23
	v_pk_mul_f32 v[14:15], v[22:23], v[14:15] op_sel_hi:[0,1]
	v_mul_f32_e32 v23, 0xbfb8aa3b, v25
	v_exp_f32_e32 v23, v23
	s_nop 0
	v_add_f32_e32 v23, 1.0, v23
	v_rcp_f32_e32 v27, v23
	v_pk_mul_f32 v[8:9], v[22:23], v[8:9] op_sel_hi:[0,1]
	v_pk_mul_f32 v[10:11], v[22:23], v[10:11] op_sel_hi:[0,1]
	v_pk_mul_f32 v[4:5], v[22:23], v[4:5] op_sel_hi:[0,1]
	v_pk_mul_f32 v[24:25], v[26:27], v[24:25]
	v_pk_mul_f32 v[6:7], v[22:23], v[6:7] op_sel_hi:[0,1]
	v_pk_mul_f32 v[14:15], v[14:15], v[24:25]
	v_cvt_pk_bf16_f32 v24, v12, v13
	v_mov_b64_e32 v[12:13], s[64:65]
	v_mad_u64_u32 v[12:13], s[0:1], v82, s97, v[12:13]
	v_lshl_add_u64 v[12:13], v[12:13], 0, v[16:17]
	v_cvt_pk_bf16_f32 v25, v14, v15
	v_lshl_add_u64 v[14:15], v[12:13], 0, v[18:19]
	s_mov_b64 s[0:1], 0x1000
	v_lshl_add_u64 v[12:13], v[14:15], 0, s[0:1]
	v_add_co_u32_e32 v14, vcc, s4, v14
	v_pk_mul_f32 v[0:1], v[22:23], v[0:1] op_sel_hi:[0,1]
	s_nop 0
	v_addc_co_u32_e32 v15, vcc, 0, v15, vcc
	global_store_dwordx2 v[14:15], v[24:25], off
	global_load_dwordx2 v[14:15], v[20:21], off offset:32
	v_pk_mul_f32 v[2:3], v[22:23], v[2:3] op_sel_hi:[0,1]
	s_mov_b64 s[0:1], 0
	s_waitcnt vmcnt(0)
	v_lshlrev_b32_e32 v16, 16, v14
	v_and_b32_e32 v17, 0xffff0000, v14
	v_mul_f32_e32 v14, 0xbfb8aa3b, v16
	v_exp_f32_e32 v14, v14
	s_nop 0
	v_add_f32_e32 v14, 1.0, v14
	v_rcp_f32_e32 v18, v14
	v_mul_f32_e32 v14, 0xbfb8aa3b, v17
	v_exp_f32_e32 v14, v14
	s_nop 0
	v_add_f32_e32 v14, 1.0, v14
	v_rcp_f32_e32 v19, v14
	v_lshlrev_b32_e32 v14, 16, v15
	v_and_b32_e32 v15, 0xffff0000, v15
	v_pk_mul_f32 v[16:17], v[18:19], v[16:17]
	s_nop 0
	v_pk_mul_f32 v[8:9], v[8:9], v[16:17]
	v_mul_f32_e32 v16, 0xbfb8aa3b, v14
	v_mul_f32_e32 v17, 0xbfb8aa3b, v15
	v_exp_f32_e32 v16, v16
	v_exp_f32_e32 v17, v17
	v_cvt_pk_bf16_f32 v8, v8, v9
	v_add_f32_e32 v16, 1.0, v16
	v_add_f32_e32 v17, 1.0, v17
	v_rcp_f32_e32 v16, v16
	v_rcp_f32_e32 v17, v17
	s_nop 0
	v_pk_mul_f32 v[14:15], v[16:17], v[14:15]
	s_nop 0
	v_pk_mul_f32 v[10:11], v[10:11], v[14:15]
	s_nop 0
	v_cvt_pk_bf16_f32 v9, v10, v11
	global_store_dwordx2 v[12:13], v[8:9], off offset:32
	global_load_dwordx2 v[8:9], v[20:21], off offset:64
	s_waitcnt vmcnt(0)
	v_lshlrev_b32_e32 v10, 16, v8
	v_and_b32_e32 v11, 0xffff0000, v8
	v_mul_f32_e32 v8, 0xbfb8aa3b, v10
	v_exp_f32_e32 v8, v8
	s_nop 0
	v_add_f32_e32 v8, 1.0, v8
	v_rcp_f32_e32 v14, v8
	v_mul_f32_e32 v8, 0xbfb8aa3b, v11
	v_exp_f32_e32 v8, v8
	s_nop 0
	v_add_f32_e32 v8, 1.0, v8
	v_rcp_f32_e32 v15, v8
	v_lshlrev_b32_e32 v8, 16, v9
	v_and_b32_e32 v9, 0xffff0000, v9
	v_pk_mul_f32 v[10:11], v[14:15], v[10:11]
	s_nop 0
	v_pk_mul_f32 v[4:5], v[4:5], v[10:11]
	v_mul_f32_e32 v10, 0xbfb8aa3b, v8
	v_mul_f32_e32 v11, 0xbfb8aa3b, v9
	v_exp_f32_e32 v10, v10
	v_exp_f32_e32 v11, v11
	v_cvt_pk_bf16_f32 v4, v4, v5
	v_add_f32_e32 v10, 1.0, v10
	v_add_f32_e32 v11, 1.0, v11
	v_rcp_f32_e32 v10, v10
	v_rcp_f32_e32 v11, v11
	s_nop 0
	v_pk_mul_f32 v[8:9], v[10:11], v[8:9]
	s_nop 0
	v_pk_mul_f32 v[6:7], v[6:7], v[8:9]
	s_nop 0
	v_cvt_pk_bf16_f32 v5, v6, v7
	global_store_dwordx2 v[12:13], v[4:5], off offset:64
	global_load_dwordx2 v[4:5], v[20:21], off offset:96
	s_waitcnt vmcnt(0)
	v_lshlrev_b32_e32 v6, 16, v4
	v_and_b32_e32 v7, 0xffff0000, v4
	v_mul_f32_e32 v4, 0xbfb8aa3b, v6
	v_exp_f32_e32 v4, v4
	s_nop 0
	v_add_f32_e32 v4, 1.0, v4
	v_rcp_f32_e32 v8, v4
	v_mul_f32_e32 v4, 0xbfb8aa3b, v7
	v_exp_f32_e32 v4, v4
	s_nop 0
	v_add_f32_e32 v4, 1.0, v4
	v_rcp_f32_e32 v9, v4
	v_lshlrev_b32_e32 v4, 16, v5
	v_and_b32_e32 v5, 0xffff0000, v5
	v_pk_mul_f32 v[6:7], v[8:9], v[6:7]
	s_nop 0
	v_pk_mul_f32 v[0:1], v[0:1], v[6:7]
	v_mul_f32_e32 v6, 0xbfb8aa3b, v4
	v_mul_f32_e32 v7, 0xbfb8aa3b, v5
	v_exp_f32_e32 v6, v6
	v_exp_f32_e32 v7, v7
	v_cvt_pk_bf16_f32 v0, v0, v1
	v_add_f32_e32 v6, 1.0, v6
	v_add_f32_e32 v7, 1.0, v7
	v_rcp_f32_e32 v6, v6
	v_rcp_f32_e32 v7, v7
	s_nop 0
	v_pk_mul_f32 v[4:5], v[6:7], v[4:5]
	s_nop 0
	v_pk_mul_f32 v[2:3], v[2:3], v[4:5]
	s_nop 0
	v_cvt_pk_bf16_f32 v1, v2, v3
	global_store_dwordx2 v[12:13], v[0:1], off offset:96
